# P10 output stores agent-scope write-through (sc1) instead of system-scope (sc0 sc1)
# speedup vs baseline: 1.0029x; 1.0029x over previous
; __device__ __forceinline__ void p10_rows(const Params& P, LAS unsigned char* lds, int G) {
;     ...
;         const int b = m >> 13; const u32x2* fr = (const u32x2*)(F + (size_t)m * DM) + lane; f32x4* outr = (f32x4*)(P.out + (size_t)m * DM) + lane; const u32x2* x1r = (const u32x2*)((const bf16_t*)(P.ws + WS_X1) + (size_t)m * DM) + lane;
;         f32x4 v[8]; u32x2 xw8[8]; float ss = 0.f;
; #pragma unroll
;         for (int j = 0; j < 8; ++j) xw8[j] = __builtin_nontemporal_load(x1r + 64 * j);
; #pragma unroll
;         for (int j = 0; j < 8; ++j) { const u32x2 w = __builtin_nontemporal_load(fr + 64 * j); v[j][0] = __uint_as_float(w.x << 16); v[j][1] = __uint_as_float(w.x & 0xffff0000u); v[j][2] = __uint_as_float(w.y << 16); v[j][3] = __uint_as_float(w.y & 0xffff0000u);
;             ss += (v[j][0] * v[j][0] + v[j][1] * v[j][1]) + (v[j][2] * v[j][2] + v[j][3] * v[j][3]); }
.LBB0_1021:
	v_add_co_u32_e32 v22, vcc, 0xf0800000, v2
	global_load_dwordx2 v[20:21], v[2:3], off nt
	global_load_dwordx2 v[18:19], v[2:3], off offset:512 nt
	global_load_dwordx2 v[16:17], v[2:3], off offset:1024 nt
	global_load_dwordx2 v[14:15], v[2:3], off offset:1536 nt
	global_load_dwordx2 v[12:13], v[2:3], off offset:2048 nt
	global_load_dwordx2 v[10:11], v[2:3], off offset:2560 nt
	global_load_dwordx2 v[8:9], v[2:3], off offset:3072 nt
	global_load_dwordx2 v[6:7], v[2:3], off offset:3584 nt
	v_addc_co_u32_e32 v23, vcc, -1, v3, vcc
	v_and_b32_e32 v31, 0xffffe000, v0
	v_add_co_u32_e32 v64, vcc, s10, v2
	global_load_dwordx2 v[22:23], v[22:23], off nt
	v_add_u32_e32 v31, v30, v31
	v_addc_co_u32_e32 v65, vcc, -1, v3, vcc
	ds_read_b128 v[32:35], v31
	ds_read_b128 v[36:39], v31 offset:1024
	ds_read_b128 v[40:43], v31 offset:2048
	ds_read_b128 v[44:47], v31 offset:3072
	ds_read_b128 v[48:51], v31 offset:4096
	ds_read_b128 v[52:55], v31 offset:5120
	ds_read_b128 v[56:59], v31 offset:6144
	ds_read_b128 v[60:63], v31 offset:7168
	global_load_dwordx2 v[66:67], v[64:65], off offset:-3584 nt
	global_load_dwordx2 v[68:69], v[64:65], off offset:-3072 nt
	global_load_dwordx2 v[70:71], v[64:65], off offset:-2560 nt
	global_load_dwordx2 v[72:73], v[64:65], off offset:-2048 nt
	global_load_dwordx2 v[74:75], v[64:65], off offset:-1536 nt
	global_load_dwordx2 v[76:77], v[64:65], off offset:-1024 nt
	global_load_dwordx2 v[78:79], v[64:65], off offset:-512 nt
	v_add_u32_e32 v0, s42, v0
	v_cmp_lt_i32_e64 s[0:1], s12, v0
	v_lshl_add_u64 v[2:3], v[2:3], 0, s[4:5]
	s_or_b64 s[8:9], s[0:1], s[8:9]
	s_waitcnt vmcnt(15)
	v_lshlrev_b32_e32 v64, 16, v20
	v_and_b32_e32 v65, 0xffff0000, v20
	v_lshlrev_b32_e32 v20, 16, v21
	s_waitcnt vmcnt(12)
	v_lshlrev_b32_e32 v84, 16, v14
	v_and_b32_e32 v85, 0xffff0000, v14
	v_lshlrev_b32_e32 v86, 16, v15
	s_waitcnt vmcnt(9)
	v_lshlrev_b32_e32 v98, 16, v9
	v_and_b32_e32 v99, 0xffff0000, v9
	s_waitcnt vmcnt(8)
	v_lshlrev_b32_e32 v102, 16, v7
	v_and_b32_e32 v103, 0xffff0000, v7
	v_and_b32_e32 v87, 0xffff0000, v15
	v_lshlrev_b32_e32 v88, 16, v12
	v_and_b32_e32 v89, 0xffff0000, v12
	s_waitcnt vmcnt(7)
	v_and_b32_e32 v7, 0xffff0000, v22
	v_and_b32_e32 v9, 0xffff0000, v23
	v_lshlrev_b32_e32 v90, 16, v13
	v_and_b32_e32 v91, 0xffff0000, v13
	v_lshlrev_b32_e32 v92, 16, v10
	v_and_b32_e32 v93, 0xffff0000, v10
	v_lshlrev_b32_e32 v94, 16, v11
	v_and_b32_e32 v95, 0xffff0000, v11
	v_lshlrev_b32_e32 v96, 16, v8
	v_and_b32_e32 v97, 0xffff0000, v8
	v_lshlrev_b32_e32 v100, 16, v6
	v_and_b32_e32 v101, 0xffff0000, v6
	v_lshlrev_b32_e32 v6, 16, v22
	v_lshlrev_b32_e32 v8, 16, v23
	v_mul_f32_e32 v10, v9, v9
	s_waitcnt vmcnt(6)
	v_lshlrev_b32_e32 v13, 16, v67
	v_lshlrev_b32_e32 v12, 16, v66
	v_and_b32_e32 v15, 0xffff0000, v67
	v_and_b32_e32 v14, 0xffff0000, v66
	s_waitcnt vmcnt(5)
	v_lshlrev_b32_e32 v22, 16, v68
	v_and_b32_e32 v23, 0xffff0000, v68
	v_lshlrev_b32_e32 v66, 16, v69
	v_and_b32_e32 v67, 0xffff0000, v69
	s_waitcnt vmcnt(4)
	v_lshlrev_b32_e32 v11, 16, v70
	v_and_b32_e32 v69, 0xffff0000, v70
	v_mul_f32_e32 v68, v7, v7
	s_waitcnt vmcnt(0)
; #define LAS __attribute__((address_space(3)))
; __device__ __forceinline__ void p10_rows(const Params& P, LAS unsigned char* lds, int G) {
;     ...
;     for (int m = blockIdx.x * 8 + wave; m < M; m += G * 8) {
;         const int b = m >> 13; const u32x2* fr = (const u32x2*)(F + (size_t)m * DM) + lane; f32x4* outr = (f32x4*)(P.out + (size_t)m * DM) + lane; const u32x2* x1r = (const u32x2*)((const bf16_t*)(P.ws + WS_X1) + (size_t)m * DM) + lane;
;         f32x4 v[8]; u32x2 xw8[8]; float ss = 0.f;
; #pragma unroll
;         for (int j = 0; j < 8; ++j) xw8[j] = __builtin_nontemporal_load(x1r + 64 * j);
; #pragma unroll
;         for (int j = 0; j < 8; ++j) { const u32x2 w = __builtin_nontemporal_load(fr + 64 * j); v[j][0] = __uint_as_float(w.x << 16); v[j][1] = __uint_as_float(w.x & 0xffff0000u); v[j][2] = __uint_as_float(w.y << 16); v[j][3] = __uint_as_float(w.y & 0xffff0000u);
;             ss += (v[j][0] * v[j][0] + v[j][1] * v[j][1]) + (v[j][2] * v[j][2] + v[j][3] * v[j][3]); }
;         const float rstd = rsqrtf(wave_sum(ss) * (1.0f / DM) + RMS_EPS);
; #pragma unroll
;         for (int j = 0; j < 8; ++j) { const f32x4 a = *(const LAS f32x4*)(TA + b * DM + 256 * j + 4 * lane); const u32x2 xw = xw8[j]; f32x4 x1; x1[0] = __uint_as_float(xw.x << 16); x1[1] = __uint_as_float(xw.x & 0xffff0000u); x1[2] = __uint_as_float(xw.y << 16); x1[3] = __uint_as_float(xw.y & 0xffff0000u); __builtin_nontemporal_store(x1 + v[j] * rstd * a, outr + 64 * j); }
;     }
	v_lshlrev_b32_e32 v111, 16, v78
	v_pk_fma_f32 v[114:115], v[8:9], v[8:9], v[10:11] op_sel_hi:[1,1,0]
	v_pk_mul_f32 v[116:117], v[14:15], v[14:15]
	v_pk_fma_f32 v[118:119], v[6:7], v[6:7], v[68:69] op_sel_hi:[1,1,0]
	v_lshlrev_b32_e32 v70, 16, v71
	v_and_b32_e32 v71, 0xffff0000, v71
	v_mov_b32_e32 v121, v11
	v_mul_f32_e32 v110, v23, v23
	v_mul_f32_e32 v122, v67, v67
	v_mov_b32_e32 v123, v111
	v_mov_b32_e32 v132, v12
	v_mov_b32_e32 v133, v14
	v_mov_b32_e32 v14, v13
	v_pk_fma_f32 v[12:13], v[12:13], v[12:13], v[116:117]
	v_mov_b32_e32 v10, v118
	v_mov_b32_e32 v120, v114
	v_mul_f32_e32 v31, v69, v69
	v_mul_f32_e32 v129, v70, v70
	v_mul_f32_e32 v131, v71, v71
	v_mov_b32_e32 v68, v11
	v_pk_add_f32 v[114:115], v[118:119], v[114:115]
	v_pk_fma_f32 v[116:117], v[22:23], v[22:23], v[110:111] op_sel_hi:[1,1,0]
	v_pk_fma_f32 v[118:119], v[66:67], v[66:67], v[122:123] op_sel_hi:[1,1,0]
	v_pk_mul_f32 v[10:11], v[10:11], v[120:121]
	v_pk_add_f32 v[12:13], v[12:13], v[12:13] op_sel:[0,1] op_sel_hi:[1,0]
	v_lshlrev_b32_e32 v105, 16, v73
	v_lshlrev_b32_e32 v104, 16, v72
	v_and_b32_e32 v73, 0xffff0000, v73
	v_and_b32_e32 v72, 0xffff0000, v72
	v_mov_b32_e32 v117, v129
	v_mov_b32_e32 v119, v131
	v_mov_b32_e32 v115, v11
	v_mov_b32_e32 v13, v31
	v_pk_mul_f32 v[124:125], v[72:73], v[72:73]
	v_pk_add_f32 v[10:11], v[116:117], v[118:119]
	v_pk_add_f32 v[12:13], v[114:115], v[12:13]
	v_lshlrev_b32_e32 v107, 16, v75
	v_lshlrev_b32_e32 v106, 16, v74
	v_and_b32_e32 v75, 0xffff0000, v75
	v_and_b32_e32 v74, 0xffff0000, v74
	v_mov_b32_e32 v134, v104
	v_mov_b32_e32 v135, v72
	v_mov_b32_e32 v72, v105
	v_pk_fma_f32 v[104:105], v[104:105], v[104:105], v[124:125]
	v_pk_add_f32 v[10:11], v[12:13], v[10:11]
	v_lshlrev_b32_e32 v108, 16, v76
	v_and_b32_e32 v109, 0xffff0000, v76
	v_lshlrev_b32_e32 v76, 16, v77
	v_and_b32_e32 v77, 0xffff0000, v77
	v_pk_mul_f32 v[126:127], v[74:75], v[74:75]
	v_pk_add_f32 v[104:105], v[104:105], v[104:105] op_sel:[0,1] op_sel_hi:[1,0]
	v_pk_add_f32 v[10:11], v[10:11], v[10:11] op_sel:[0,1] op_sel_hi:[1,0]
	v_and_b32_e32 v113, 0xffff0000, v78
	v_lshlrev_b32_e32 v78, 16, v79
	v_and_b32_e32 v79, 0xffff0000, v79
	v_mul_f32_e32 v128, v109, v109
	v_mul_f32_e32 v130, v77, v77
	v_mov_b32_e32 v136, v106
	v_mov_b32_e32 v137, v74
	v_mov_b32_e32 v74, v107
	v_pk_fma_f32 v[106:107], v[106:107], v[106:107], v[126:127]
	v_mov_b32_e32 v122, v104
	v_mov_b32_e32 v110, v10
	v_mul_f32_e32 v138, v113, v113
	v_mul_f32_e32 v139, v78, v78
	v_mul_f32_e32 v140, v79, v79
	v_pk_fma_f32 v[124:125], v[108:109], v[108:109], v[128:129] op_sel_hi:[1,1,0]
	v_pk_fma_f32 v[126:127], v[76:77], v[76:77], v[130:131] op_sel_hi:[1,1,0]
	v_pk_add_f32 v[106:107], v[106:107], v[106:107] op_sel:[0,1] op_sel_hi:[1,0]
	v_pk_add_f32 v[10:11], v[10:11], v[104:105]
	v_pk_mul_f32 v[12:13], v[110:111], v[122:123]
	v_mov_b32_e32 v125, v139
	v_mov_b32_e32 v127, v140
	v_mov_b32_e32 v107, v138
	v_mov_b32_e32 v11, v13
	v_pk_add_f32 v[116:117], v[124:125], v[126:127]
	v_pk_add_f32 v[10:11], v[10:11], v[106:107]
	v_and_b32_e32 v21, 0xffff0000, v21
	v_pk_add_f32 v[10:11], v[10:11], v[116:117]
	v_mov_b32_e32 v112, v111
	v_add_f32_e32 v10, v10, v11
	s_nop 1
	v_add_f32_dpp v10, v10, v10 quad_perm:[1,0,3,2] row_mask:0xf bank_mask:0xf
	v_lshlrev_b32_e32 v80, 16, v18
	v_and_b32_e32 v81, 0xffff0000, v18
	v_lshlrev_b32_e32 v18, 16, v19
	v_and_b32_e32 v19, 0xffff0000, v19
	s_nop 1
	v_add_f32_dpp v10, v10, v10 quad_perm:[2,3,0,1] row_mask:0xf bank_mask:0xf
	v_lshlrev_b32_e32 v82, 16, v16
	v_and_b32_e32 v83, 0xffff0000, v16
	v_lshlrev_b32_e32 v16, 16, v17
	v_and_b32_e32 v17, 0xffff0000, v17
	s_nop 1
	v_add_f32_dpp v10, v10, v10 row_half_mirror row_mask:0xf bank_mask:0xf
	s_nop 1
	v_add_f32_dpp v10, v10, v10 row_mirror row_mask:0xf bank_mask:0xf
	v_mov_b32_e32 v11, v10
	s_nop 1
	v_permlane16_swap_b32_e32 v11, v10
	v_add_f32_e32 v10, v10, v11
	v_mov_b32_e32 v11, v10
	s_nop 1
	v_permlane32_swap_b32_e32 v11, v10
	v_add_f32_e32 v10, v10, v11
	s_waitcnt lgkmcnt(0)
	v_fmamk_f32 v10, v10, 0x3a000000, v1
	v_mul_f32_e32 v11, 0x4b800000, v10
	v_cmp_gt_f32_e32 vcc, s11, v10
	s_nop 1
	v_cndmask_b32_e32 v10, v10, v11, vcc
	v_rsq_f32_e32 v10, v10
	s_nop 0
	v_mul_f32_e32 v11, 0x45800000, v10
	v_cndmask_b32_e32 v10, v10, v11, vcc
	v_pk_mul_f32 v[6:7], v[10:11], v[6:7] op_sel_hi:[0,1]
	v_pk_mul_f32 v[8:9], v[10:11], v[8:9] op_sel_hi:[0,1]
	v_pk_mul_f32 v[104:105], v[10:11], v[132:133] op_sel_hi:[0,1]
	v_pk_mul_f32 v[12:13], v[10:11], v[14:15] op_sel_hi:[0,1]
	v_pk_mul_f32 v[14:15], v[10:11], v[22:23] op_sel_hi:[0,1]
	v_pk_mul_f32 v[22:23], v[10:11], v[66:67] op_sel_hi:[0,1]
	v_pk_mul_f32 v[66:67], v[68:69], v[10:11] op_sel_hi:[1,0]
	v_pk_mul_f32 v[68:69], v[70:71], v[10:11] op_sel_hi:[1,0]
	v_pk_mul_f32 v[70:71], v[10:11], v[134:135] op_sel_hi:[0,1]
	v_pk_mul_f32 v[72:73], v[10:11], v[72:73] op_sel_hi:[0,1]
	v_pk_mul_f32 v[106:107], v[10:11], v[136:137] op_sel_hi:[0,1]
	v_pk_mul_f32 v[74:75], v[10:11], v[74:75] op_sel_hi:[0,1]
	v_pk_mul_f32 v[108:109], v[10:11], v[108:109] op_sel_hi:[0,1]
	v_pk_mul_f32 v[76:77], v[10:11], v[76:77] op_sel_hi:[0,1]
	v_pk_mul_f32 v[110:111], v[112:113], v[10:11] op_sel_hi:[1,0]
	v_pk_mul_f32 v[78:79], v[78:79], v[10:11] op_sel_hi:[1,0]
	v_pk_fma_f32 v[8:9], v[34:35], v[8:9], v[20:21]
	v_pk_fma_f32 v[6:7], v[32:33], v[6:7], v[64:65]
	v_pk_fma_f32 v[12:13], v[38:39], v[12:13], v[18:19]
	v_pk_fma_f32 v[10:11], v[36:37], v[104:105], v[80:81]
	v_pk_fma_f32 v[16:17], v[42:43], v[22:23], v[16:17]
	v_pk_fma_f32 v[14:15], v[40:41], v[14:15], v[82:83]
	v_pk_fma_f32 v[20:21], v[46:47], v[68:69], v[86:87]
	v_pk_fma_f32 v[18:19], v[44:45], v[66:67], v[84:85]
	v_pk_fma_f32 v[34:35], v[50:51], v[72:73], v[90:91]
	v_pk_fma_f32 v[32:33], v[48:49], v[70:71], v[88:89]
	v_pk_fma_f32 v[38:39], v[54:55], v[74:75], v[94:95]
	v_pk_fma_f32 v[36:37], v[52:53], v[106:107], v[92:93]
	v_pk_fma_f32 v[42:43], v[58:59], v[76:77], v[98:99]
	v_pk_fma_f32 v[40:41], v[56:57], v[108:109], v[96:97]
	v_pk_fma_f32 v[46:47], v[62:63], v[78:79], v[102:103]
	v_pk_fma_f32 v[44:45], v[60:61], v[110:111], v[100:101]
	global_store_dwordx4 v[4:5], v[6:9], off offset:-4096 sc1
	global_store_dwordx4 v[4:5], v[10:13], off offset:-3072 sc1
	global_store_dwordx4 v[4:5], v[14:17], off offset:-2048 sc1
	global_store_dwordx4 v[4:5], v[18:21], off offset:-1024 sc1
	global_store_dwordx4 v[4:5], v[32:35], off sc1
	global_store_dwordx4 v[4:5], v[36:39], off offset:1024 sc1
	global_store_dwordx4 v[4:5], v[40:43], off offset:2048 sc1
	global_store_dwordx4 v[4:5], v[44:47], off offset:3072 sc1
	v_lshl_add_u64 v[4:5], v[4:5], 0, s[6:7]
	s_andn2_b64 exec, exec, s[8:9]
	s_cbranch_execnz .LBB0_1021
